# attention loops: bias-table reads of the second key tile issued as soon as half of the first tile's registers are consumed (one LDS round trip less per near iteration)
# baseline (speedup 1.0000x reference)
; #define NEGINF (-__builtin_inff())
; DI int crow(int i, int h) { return (i & 3) + 8 * (i >> 2) + 4 * h; }
; DI void bias16(const unsigned char* blut, const float* tblh, const int (&dist)[16], float (&bv)[16]) {
;   int bk[16];
; #pragma unroll
;   for (int i = 0; i < 16; ++i) { const int d = dist[i] < 0 ? 0 : (dist[i] > 2048 ? 2048 : dist[i]); bk[i] = blut[d]; }
; #pragma unroll
;   for (int i = 0; i < 16; ++i) asm volatile("" : "+v"(bk[i]));
; #pragma unroll
;   for (int i = 0; i < 16; ++i) bv[i] = tblh[bk[i]];
; #pragma unroll
;   for (int i = 0; i < 16; ++i) asm volatile("" : "+v"(bv[i]));
; }
; DI void nsa_win_item(const Params& p, int b, int head, int qb, const unsigned char* blut, const float* tbl) {
;     ...
;     attn_loop(st, qf, k0, qb, 32,
;       [&](int kt) { return K + (size_t)kt * 2048 + (h * 32 + r) * 8; },
;       [&](int kt) { return Vt + (size_t)kt * 2048 + (h * 32 + r) * 4; },
;       [&](int kt) { return true; },
;       [&](int kt, const f32x16& s, float (&lg)[16]) {
;         int dist[16]; float bv[16];
; #pragma unroll
;         for (int i = 0; i < 16; ++i) dist[i] = t - (kt * 32 + crow(i, h));
;         bias16(blut, tblh, dist, bv);
; #pragma unroll
;         for (int i = 0; i < 16; ++i) lg[i] = (dist[i] >= 0 && dist[i] < 512) ? s[i] + bv[i] : NEGINF;
;       });
.Lawin6_loop:
	s_waitcnt vmcnt(2)
	s_barrier
	s_lshr_b32 s23, s56, 1
	s_add_u32 s23, s23, 2
	s_sub_u32 s61, s64, 0x4000
	s_cmp_lt_u32 s61, 0x10000
	s_cselect_b32 s61, 0x18000, s61
	s_lshr_b32 s24, s59, 1
	s_min_u32 s24, s23, s24
	s_lshl_b32 s26, s24, 13
	s_lshl_b32 s24, s58, 10
	s_add_u32 s26, s26, s24
	s_mov_b32 s27, 0
	v_lshl_add_u64 v[248:249], v[116:117], 0, s[26:27]
	v_lshl_add_u64 v[250:251], v[114:115], 0, s[26:27]
	v_add_co_u32_e32 v250, vcc, v250, v247
	v_addc_co_u32_e32 v251, vcc, 0, v251, vcc
	s_add_u32 s24, s24, s61
	s_mov_b32 m0, s24
	s_nop 0
	global_load_lds_dwordx4 v[248:249], off
	s_add_u32 s24, s24, 0x2000
	s_mov_b32 m0, s24
	s_nop 0
	global_load_lds_dwordx4 v[250:251], off
	s_cmp_le_u32 s56, s60
	s_cbranch_scc0 .Lawin6_skip
	s_add_u32 s24, s56, 1
	s_cmp_ge_u32 s24, s65
	s_cbranch_scc0 .Lawin6_skip
	v_lshl_add_u32 v248, v247, 1, s64
	ds_read_b128 v[80:83], v248 offset:0
	ds_read_b128 v[96:99], v248 offset:4096
	ds_read_b128 v[84:87], v248 offset:1024
	ds_read_b128 v[100:103], v248 offset:5120
	ds_read_b128 v[88:91], v248 offset:2048
	ds_read_b128 v[104:107], v248 offset:6144
	ds_read_b128 v[92:95], v248 offset:3072
	ds_read_b128 v[108:111], v248 offset:7168
	s_sub_i32 s61, s60, s56
	s_waitcnt lgkmcnt(6)
	v_mfma_f32_32x32x16_bf16 v[32:47], v[80:83], v[64:67], 0
	v_mfma_f32_32x32x16_bf16 v[48:63], v[96:99], v[64:67], 0
	s_waitcnt lgkmcnt(4)
	v_mfma_f32_32x32x16_bf16 v[32:47], v[84:87], v[68:71], v[32:47]
	v_mfma_f32_32x32x16_bf16 v[48:63], v[100:103], v[68:71], v[48:63]
	s_waitcnt lgkmcnt(2)
	v_mfma_f32_32x32x16_bf16 v[32:47], v[88:91], v[72:75], v[32:47]
	v_mfma_f32_32x32x16_bf16 v[48:63], v[104:107], v[72:75], v[48:63]
	s_waitcnt lgkmcnt(0)
	v_mfma_f32_32x32x16_bf16 v[32:47], v[92:95], v[76:79], v[32:47]
	v_mfma_f32_32x32x16_bf16 v[48:63], v[108:111], v[76:79], v[48:63]
	v_add_u32_e32 v250, s64, v247
	ds_read_b64 v[146:147], v250 offset:8192
	ds_read_b64 v[148:149], v250 offset:8704
	ds_read_b64 v[150:151], v250 offset:9216
	ds_read_b64 v[152:153], v250 offset:9728
	ds_read_b64 v[154:155], v250 offset:10240
	ds_read_b64 v[156:157], v250 offset:10752
	ds_read_b64 v[158:159], v250 offset:11264
	ds_read_b64 v[160:161], v250 offset:11776
	ds_read_b64 v[162:163], v250 offset:12288
	ds_read_b64 v[164:165], v250 offset:12800
	ds_read_b64 v[166:167], v250 offset:13312
	ds_read_b64 v[168:169], v250 offset:13824
	ds_read_b64 v[170:171], v250 offset:14336
	ds_read_b64 v[172:173], v250 offset:14848
	ds_read_b64 v[174:175], v250 offset:15360
	ds_read_b64 v[176:177], v250 offset:15872
	s_cmp_ge_i32 s61, 50
	s_cbranch_scc1 .Lawin6_far
	s_lshl_b32 s23, s61, 5
	v_add_u32_e32 v241, s23, v222
	v_lshl_add_u32 v244, v241, 2, v242
	v_subrev_u32_e32 v245, 128, v244
	ds_read_b32 v224, v244 offset:108
	ds_read_b32 v225, v244 offset:104
	ds_read_b32 v226, v244 offset:100
	ds_read_b32 v227, v244 offset:96
	ds_read_b32 v228, v244 offset:76
	ds_read_b32 v229, v244 offset:72
	ds_read_b32 v230, v244 offset:68
	ds_read_b32 v231, v244 offset:64
	ds_read_b32 v232, v244 offset:44
	ds_read_b32 v233, v244 offset:40
	ds_read_b32 v234, v244 offset:36
	ds_read_b32 v235, v244 offset:32
	ds_read_b32 v236, v244 offset:12
	ds_read_b32 v237, v244 offset:8
	ds_read_b32 v238, v244 offset:4
	ds_read_b32 v239, v244 offset:0
	s_waitcnt lgkmcnt(8)
	v_add_f32_e32 v32, v32, v224
	v_add_f32_e32 v33, v33, v225
	v_add_f32_e32 v34, v34, v226
	v_add_f32_e32 v35, v35, v227
	v_add_f32_e32 v36, v36, v228
	v_add_f32_e32 v37, v37, v229
	v_add_f32_e32 v38, v38, v230
	v_add_f32_e32 v39, v39, v231
	ds_read_b32 v224, v245 offset:108
	ds_read_b32 v225, v245 offset:104
	ds_read_b32 v226, v245 offset:100
	ds_read_b32 v227, v245 offset:96
	ds_read_b32 v228, v245 offset:76
	ds_read_b32 v229, v245 offset:72
	ds_read_b32 v230, v245 offset:68
	ds_read_b32 v231, v245 offset:64
	s_waitcnt lgkmcnt(8)
	v_add_f32_e32 v40, v40, v232
	v_add_f32_e32 v41, v41, v233
	v_add_f32_e32 v42, v42, v234
	v_add_f32_e32 v43, v43, v235
	v_add_f32_e32 v44, v44, v236
	v_add_f32_e32 v45, v45, v237
	v_add_f32_e32 v46, v46, v238
	v_add_f32_e32 v47, v47, v239
	ds_read_b32 v232, v245 offset:44
	ds_read_b32 v233, v245 offset:40
	ds_read_b32 v234, v245 offset:36
	ds_read_b32 v235, v245 offset:32
	ds_read_b32 v236, v245 offset:12
	ds_read_b32 v237, v245 offset:8
	ds_read_b32 v238, v245 offset:4
	ds_read_b32 v239, v245 offset:0
	s_waitcnt lgkmcnt(8)
	v_add_f32_e32 v48, v48, v224
	v_add_f32_e32 v49, v49, v225
	v_add_f32_e32 v50, v50, v226
	v_add_f32_e32 v51, v51, v227
	v_add_f32_e32 v52, v52, v228
	v_add_f32_e32 v53, v53, v229
	v_add_f32_e32 v54, v54, v230
	v_add_f32_e32 v55, v55, v231
	s_waitcnt lgkmcnt(0)
	v_add_f32_e32 v56, v56, v232
	v_add_f32_e32 v57, v57, v233
	v_add_f32_e32 v58, v58, v234
	v_add_f32_e32 v59, v59, v235
	v_add_f32_e32 v60, v60, v236
	v_add_f32_e32 v61, v61, v237
	v_add_f32_e32 v62, v62, v238
	v_add_f32_e32 v63, v63, v239
	s_cmp_ge_i32 s61, 15
	s_cbranch_scc0 .Lawin6_nowin
; #define NEGINF (-__builtin_inff())
; DI int crow(int i, int h) { return (i & 3) + 8 * (i >> 2) + 4 * h; }
; DI void nsa_win_item(const Params& p, int b, int head, int qb, const unsigned char* blut, const float* tbl) {
;     ...
;       [&](int kt, const f32x16& s, float (&lg)[16]) {
;         int dist[16]; float bv[16];
; #pragma unroll
;         for (int i = 0; i < 16; ++i) dist[i] = t - (kt * 32 + crow(i, h));
;         bias16(blut, tblh, dist, bv);
; #pragma unroll
;         for (int i = 0; i < 16; ++i) lg[i] = (dist[i] >= 0 && dist[i] < 512) ? s[i] + bv[i] : NEGINF;
;       });
	v_subrev_u32_e32 v246, 32, v241
	v_cmp_gt_i32_e32 vcc, 0x200, v241
	s_nop 1
	v_cndmask_b32_e32 v32, v199, v32, vcc
	v_cmp_gt_i32_e32 vcc, 0x201, v241
	s_nop 1
	v_cndmask_b32_e32 v33, v199, v33, vcc
	v_cmp_gt_i32_e32 vcc, 0x202, v241
	s_nop 1
	v_cndmask_b32_e32 v34, v199, v34, vcc
	v_cmp_gt_i32_e32 vcc, 0x203, v241
	s_nop 1
	v_cndmask_b32_e32 v35, v199, v35, vcc
	v_cmp_gt_i32_e32 vcc, 0x208, v241
	s_nop 1
	v_cndmask_b32_e32 v36, v199, v36, vcc
	v_cmp_gt_i32_e32 vcc, 0x209, v241
	s_nop 1
	v_cndmask_b32_e32 v37, v199, v37, vcc
	v_cmp_gt_i32_e32 vcc, 0x20a, v241
	s_nop 1
	v_cndmask_b32_e32 v38, v199, v38, vcc
	v_cmp_gt_i32_e32 vcc, 0x20b, v241
	s_nop 1
	v_cndmask_b32_e32 v39, v199, v39, vcc
	v_cmp_gt_i32_e32 vcc, 0x210, v241
	s_nop 1
	v_cndmask_b32_e32 v40, v199, v40, vcc
	v_cmp_gt_i32_e32 vcc, 0x211, v241
	s_nop 1
	v_cndmask_b32_e32 v41, v199, v41, vcc
	v_cmp_gt_i32_e32 vcc, 0x212, v241
	s_nop 1
	v_cndmask_b32_e32 v42, v199, v42, vcc
	v_cmp_gt_i32_e32 vcc, 0x213, v241
	s_nop 1
	v_cndmask_b32_e32 v43, v199, v43, vcc
	v_cmp_gt_i32_e32 vcc, 0x218, v241
	s_nop 1
	v_cndmask_b32_e32 v44, v199, v44, vcc
	v_cmp_gt_i32_e32 vcc, 0x219, v241
	s_nop 1
	v_cndmask_b32_e32 v45, v199, v45, vcc
	v_cmp_gt_i32_e32 vcc, 0x21a, v241
	s_nop 1
	v_cndmask_b32_e32 v46, v199, v46, vcc
	v_cmp_gt_i32_e32 vcc, 0x21b, v241
	s_nop 1
	v_cndmask_b32_e32 v47, v199, v47, vcc
	v_cmp_gt_i32_e32 vcc, 0x200, v246
	s_nop 1
	v_cndmask_b32_e32 v48, v199, v48, vcc
	v_cmp_gt_i32_e32 vcc, 0x201, v246
	s_nop 1
	v_cndmask_b32_e32 v49, v199, v49, vcc
	v_cmp_gt_i32_e32 vcc, 0x202, v246
	s_nop 1
	v_cndmask_b32_e32 v50, v199, v50, vcc
	v_cmp_gt_i32_e32 vcc, 0x203, v246
	s_nop 1
	v_cndmask_b32_e32 v51, v199, v51, vcc
	v_cmp_gt_i32_e32 vcc, 0x208, v246
	s_nop 1
	v_cndmask_b32_e32 v52, v199, v52, vcc
	v_cmp_gt_i32_e32 vcc, 0x209, v246
	s_nop 1
	v_cndmask_b32_e32 v53, v199, v53, vcc
	v_cmp_gt_i32_e32 vcc, 0x20a, v246
	s_nop 1
	v_cndmask_b32_e32 v54, v199, v54, vcc
	v_cmp_gt_i32_e32 vcc, 0x20b, v246
	s_nop 1
	v_cndmask_b32_e32 v55, v199, v55, vcc
	v_cmp_gt_i32_e32 vcc, 0x210, v246
	s_nop 1
	v_cndmask_b32_e32 v56, v199, v56, vcc
	v_cmp_gt_i32_e32 vcc, 0x211, v246
	s_nop 1
	v_cndmask_b32_e32 v57, v199, v57, vcc
	v_cmp_gt_i32_e32 vcc, 0x212, v246
	s_nop 1
	v_cndmask_b32_e32 v58, v199, v58, vcc
	v_cmp_gt_i32_e32 vcc, 0x213, v246
	s_nop 1
	v_cndmask_b32_e32 v59, v199, v59, vcc
	v_cmp_gt_i32_e32 vcc, 0x218, v246
	s_nop 1
	v_cndmask_b32_e32 v60, v199, v60, vcc
	v_cmp_gt_i32_e32 vcc, 0x219, v246
	s_nop 1
	v_cndmask_b32_e32 v61, v199, v61, vcc
	v_cmp_gt_i32_e32 vcc, 0x21a, v246
	s_nop 1
	v_cndmask_b32_e32 v62, v199, v62, vcc
	v_cmp_gt_i32_e32 vcc, 0x21b, v246
	s_nop 1
	v_cndmask_b32_e32 v63, v199, v63, vcc

; #define MFMA32(a, b, c) __builtin_amdgcn_mfma_f32_32x32x16_bf16((a), (b), (c), 0, 0, 0)
; template <class KP, class VP, class ACT, class FILL>
; DI void attn_loop(AttnSt& st, const bf16x8 (&qf)[4], int k0, int k1, size_t vstride, KP kp, VP vp, ACT act, FILL fill) {
;     ...
;   for (int kt = k0; kt <= k1; ++kt) {
;     const int kn = (kt < k1) ? kt + 1 : k1;
;     const int kn2 = (kt + 2 <= k1) ? kt + 2 : k1;
;     {
;       const bf16_t* v0 = vp(kn);
; #pragma unroll
;       for (int j = 0; j < 8; ++j) nxt.v[j] = *(const s16x4*)(v0 + 256 * j);
;     }
;     bf16x8 k2[4];
;     {
;       const bf16_t* krow = kp(kn2);
; #pragma unroll
;       for (int ss = 0; ss < 4; ++ss) k2[ss] = *(const bf16x8*)(krow + 512 * ss);
;     }
;     f32x16 s_next;
; #pragma unroll
;     for (int i = 0; i < 16; ++i) s_next[i] = 0.f;
; #pragma unroll
;     for (int ss = 0; ss < 4; ++ss) s_next = MFMA32(nxt.k[ss], qf[ss], s_next);
; DI void nsa_main_item(const Params& p, int b, int head, int qb, const unsigned char* blut, const float* tbl) {
;     ...
;     attn_loop(st, qf, 0, qb, 32,
;       [&](int kt) { return K + (size_t)kt * 2048 + (h * 32 + r) * 8; },
;       [&](int kt) { return Vt + (size_t)kt * 2048 + (h * 32 + r) * 4; },
;       [&](int kt) { return __ballot((selm >> (kt >> 1)) & 1ull) != 0ull; },
;       [&](int kt, const f32x16& s, float (&lg)[16]) {
;         const bool bs = (selm >> (kt >> 1)) & 1ull;
.Lasel_loop:
	s_waitcnt vmcnt(2)
	s_barrier
	s_lshr_b32 s23, s56, 1
	s_add_u32 s23, s23, 2
	s_sub_u32 s61, s100, 0x4000
	s_cmp_lt_u32 s61, 0x10000
	s_cselect_b32 s61, 0x18000, s61
	s_lshr_b32 s24, s59, 1
	s_min_u32 s24, s23, s24
	s_lshl_b32 s26, s24, 13
	s_lshl_b32 s24, s58, 10
	s_add_u32 s26, s26, s24
	s_mov_b32 s27, 0
	v_lshl_add_u64 v[248:249], v[148:149], 0, s[26:27]
	v_lshl_add_u64 v[250:251], v[170:171], 0, s[26:27]
	v_add_co_u32_e32 v250, vcc, v250, v247
	v_addc_co_u32_e32 v251, vcc, 0, v251, vcc
	s_add_u32 s24, s24, s61
	s_mov_b32 m0, s24
	s_nop 0
	global_load_lds_dwordx4 v[248:249], off
	s_add_u32 s24, s24, 0x2000
	s_mov_b32 m0, s24
	s_nop 0
	global_load_lds_dwordx4 v[250:251], off
	s_cmp_le_u32 s56, s60
	s_cbranch_scc0 .Lasel_skip
	v_lshl_add_u32 v248, v247, 1, s100
	ds_read_b128 v[96:99], v248 offset:0
	ds_read_b128 v[112:115], v248 offset:4096
	ds_read_b128 v[100:103], v248 offset:1024
	ds_read_b128 v[116:119], v248 offset:5120
	ds_read_b128 v[104:107], v248 offset:2048
	ds_read_b128 v[120:123], v248 offset:6144
	ds_read_b128 v[108:111], v248 offset:3072
	ds_read_b128 v[124:127], v248 offset:7168
	s_sub_i32 s61, s60, s56
	s_lshr_b32 s23, s56, 1
	v_lshrrev_b64 v[248:249], s23, v[168:169]
	v_and_b32_e32 v248, 1, v248
	v_cmp_eq_u32_e64 s[62:63], 1, v248
	s_waitcnt lgkmcnt(6)
	v_mfma_f32_32x32x16_bf16 v[32:47], v[96:99], v[80:83], 0
	v_mfma_f32_32x32x16_bf16 v[48:63], v[112:115], v[80:83], 0
	s_waitcnt lgkmcnt(4)
	v_mfma_f32_32x32x16_bf16 v[32:47], v[100:103], v[84:87], v[32:47]
	v_mfma_f32_32x32x16_bf16 v[48:63], v[116:119], v[84:87], v[48:63]
	s_waitcnt lgkmcnt(2)
	v_mfma_f32_32x32x16_bf16 v[32:47], v[104:107], v[88:91], v[32:47]
	v_mfma_f32_32x32x16_bf16 v[48:63], v[120:123], v[88:91], v[48:63]
	s_waitcnt lgkmcnt(0)
	v_mfma_f32_32x32x16_bf16 v[32:47], v[108:111], v[92:95], v[32:47]
	v_mfma_f32_32x32x16_bf16 v[48:63], v[124:127], v[92:95], v[48:63]
	v_add_u32_e32 v250, s100, v247
	ds_read_b64 v[64:65], v250 offset:8192
	ds_read_b64 v[66:67], v250 offset:8704
	ds_read_b64 v[68:69], v250 offset:9216
	ds_read_b64 v[70:71], v250 offset:9728
	ds_read_b64 v[72:73], v250 offset:10240
	ds_read_b64 v[74:75], v250 offset:10752
	ds_read_b64 v[76:77], v250 offset:11264
	ds_read_b64 v[78:79], v250 offset:11776
	ds_read_b64 v[172:173], v250 offset:12288
	ds_read_b64 v[174:175], v250 offset:12800
	ds_read_b64 v[176:177], v250 offset:13312
	ds_read_b64 v[178:179], v250 offset:13824
	ds_read_b64 v[180:181], v250 offset:14336
	ds_read_b64 v[182:183], v250 offset:14848
	ds_read_b64 v[184:185], v250 offset:15360
	ds_read_b64 v[186:187], v250 offset:15872
	s_cmp_ge_i32 s61, 50
	s_cbranch_scc1 .Lasel_far
; #define NEGINF (-__builtin_inff())
; DI int crow(int i, int h) { return (i & 3) + 8 * (i >> 2) + 4 * h; }
; DI void nsa_main_item(const Params& p, int b, int head, int qb, const unsigned char* blut, const float* tbl) {
;     ...
;           int dist[16]; float bv[16];
; #pragma unroll
;           for (int i = 0; i < 16; ++i) dist[i] = t - (kt * 32 + crow(i, h));
;           bias16(blut, tblh, dist, bv);
; #pragma unroll
;           for (int i = 0; i < 16; ++i) lg[i] = (bs && dist[i] >= 0) ? s[i] + bv[i] : NEGINF;
	s_lshl_b32 s23, s61, 5
	v_add_u32_e32 v241, s23, v221
	v_lshl_add_u32 v244, v241, 2, v242
	v_subrev_u32_e32 v245, 128, v244
	ds_read_b32 v224, v244 offset:108
	ds_read_b32 v225, v244 offset:104
	ds_read_b32 v226, v244 offset:100
	ds_read_b32 v227, v244 offset:96
	ds_read_b32 v228, v244 offset:76
	ds_read_b32 v229, v244 offset:72
	ds_read_b32 v230, v244 offset:68
	ds_read_b32 v231, v244 offset:64
	ds_read_b32 v232, v244 offset:44
	ds_read_b32 v233, v244 offset:40
	ds_read_b32 v234, v244 offset:36
	ds_read_b32 v235, v244 offset:32
	ds_read_b32 v236, v244 offset:12
	ds_read_b32 v237, v244 offset:8
	ds_read_b32 v238, v244 offset:4
	ds_read_b32 v239, v244 offset:0
	s_waitcnt lgkmcnt(8)
	v_add_f32_e32 v32, v32, v224
	v_add_f32_e32 v33, v33, v225
	v_add_f32_e32 v34, v34, v226
	v_add_f32_e32 v35, v35, v227
	v_add_f32_e32 v36, v36, v228
	v_add_f32_e32 v37, v37, v229
	v_add_f32_e32 v38, v38, v230
	v_add_f32_e32 v39, v39, v231
	ds_read_b32 v224, v245 offset:108
	ds_read_b32 v225, v245 offset:104
	ds_read_b32 v226, v245 offset:100
	ds_read_b32 v227, v245 offset:96
	ds_read_b32 v228, v245 offset:76
	ds_read_b32 v229, v245 offset:72
	ds_read_b32 v230, v245 offset:68
	ds_read_b32 v231, v245 offset:64
	s_waitcnt lgkmcnt(8)
	v_add_f32_e32 v40, v40, v232
	v_add_f32_e32 v41, v41, v233
	v_add_f32_e32 v42, v42, v234
	v_add_f32_e32 v43, v43, v235
	v_add_f32_e32 v44, v44, v236
	v_add_f32_e32 v45, v45, v237
	v_add_f32_e32 v46, v46, v238
	v_add_f32_e32 v47, v47, v239
	ds_read_b32 v232, v245 offset:44
	ds_read_b32 v233, v245 offset:40
	ds_read_b32 v234, v245 offset:36
	ds_read_b32 v235, v245 offset:32
	ds_read_b32 v236, v245 offset:12
	ds_read_b32 v237, v245 offset:8
	ds_read_b32 v238, v245 offset:4
	ds_read_b32 v239, v245 offset:0
	s_waitcnt lgkmcnt(8)
	v_add_f32_e32 v48, v48, v224
	v_add_f32_e32 v49, v49, v225
	v_add_f32_e32 v50, v50, v226
	v_add_f32_e32 v51, v51, v227
	v_add_f32_e32 v52, v52, v228
	v_add_f32_e32 v53, v53, v229
	v_add_f32_e32 v54, v54, v230
	v_add_f32_e32 v55, v55, v231
	s_waitcnt lgkmcnt(0)
	v_add_f32_e32 v56, v56, v232
	v_add_f32_e32 v57, v57, v233
	v_add_f32_e32 v58, v58, v234
	v_add_f32_e32 v59, v59, v235
	v_add_f32_e32 v60, v60, v236
	v_add_f32_e32 v61, v61, v237
	v_add_f32_e32 v62, v62, v238
	v_add_f32_e32 v63, v63, v239
	s_cmp_ge_i32 s61, 2
	s_cbranch_scc1 .Lasel_softmax
	v_subrev_u32_e32 v246, 32, v241
	v_cmp_le_i32_e32 vcc, 0, v241
	s_nop 1
	v_cndmask_b32_e32 v32, v199, v32, vcc
	v_cmp_le_i32_e32 vcc, 1, v241
	s_nop 1
	v_cndmask_b32_e32 v33, v199, v33, vcc
	v_cmp_le_i32_e32 vcc, 2, v241
	s_nop 1
	v_cndmask_b32_e32 v34, v199, v34, vcc
	v_cmp_le_i32_e32 vcc, 3, v241
	s_nop 1
	v_cndmask_b32_e32 v35, v199, v35, vcc
	v_cmp_le_i32_e32 vcc, 8, v241
	s_nop 1
	v_cndmask_b32_e32 v36, v199, v36, vcc
	v_cmp_le_i32_e32 vcc, 9, v241
	s_nop 1
	v_cndmask_b32_e32 v37, v199, v37, vcc
	v_cmp_le_i32_e32 vcc, 10, v241
	s_nop 1
	v_cndmask_b32_e32 v38, v199, v38, vcc
	v_cmp_le_i32_e32 vcc, 11, v241
	s_nop 1
	v_cndmask_b32_e32 v39, v199, v39, vcc
	v_cmp_le_i32_e32 vcc, 16, v241
	s_nop 1
	v_cndmask_b32_e32 v40, v199, v40, vcc
	v_cmp_le_i32_e32 vcc, 17, v241
	s_nop 1
	v_cndmask_b32_e32 v41, v199, v41, vcc
	v_cmp_le_i32_e32 vcc, 18, v241
	s_nop 1
	v_cndmask_b32_e32 v42, v199, v42, vcc
	v_cmp_le_i32_e32 vcc, 19, v241
	s_nop 1
	v_cndmask_b32_e32 v43, v199, v43, vcc
	v_cmp_le_i32_e32 vcc, 24, v241
	s_nop 1
	v_cndmask_b32_e32 v44, v199, v44, vcc
	v_cmp_le_i32_e32 vcc, 25, v241
	s_nop 1
	v_cndmask_b32_e32 v45, v199, v45, vcc
	v_cmp_le_i32_e32 vcc, 26, v241
	s_nop 1
	v_cndmask_b32_e32 v46, v199, v46, vcc
	v_cmp_le_i32_e32 vcc, 27, v241
	s_nop 1
	v_cndmask_b32_e32 v47, v199, v47, vcc
	v_cmp_le_i32_e32 vcc, 0, v246
	s_nop 1
	v_cndmask_b32_e32 v48, v199, v48, vcc
	v_cmp_le_i32_e32 vcc, 1, v246
	s_nop 1
	v_cndmask_b32_e32 v49, v199, v49, vcc
	v_cmp_le_i32_e32 vcc, 2, v246
	s_nop 1
	v_cndmask_b32_e32 v50, v199, v50, vcc
	v_cmp_le_i32_e32 vcc, 3, v246
	s_nop 1
	v_cndmask_b32_e32 v51, v199, v51, vcc
	v_cmp_le_i32_e32 vcc, 8, v246
	s_nop 1
	v_cndmask_b32_e32 v52, v199, v52, vcc
	v_cmp_le_i32_e32 vcc, 9, v246
	s_nop 1
	v_cndmask_b32_e32 v53, v199, v53, vcc
	v_cmp_le_i32_e32 vcc, 10, v246
	s_nop 1
	v_cndmask_b32_e32 v54, v199, v54, vcc
	v_cmp_le_i32_e32 vcc, 11, v246
	s_nop 1
	v_cndmask_b32_e32 v55, v199, v55, vcc
	v_cmp_le_i32_e32 vcc, 16, v246
	s_nop 1
	v_cndmask_b32_e32 v56, v199, v56, vcc
	v_cmp_le_i32_e32 vcc, 17, v246
	s_nop 1
	v_cndmask_b32_e32 v57, v199, v57, vcc
	v_cmp_le_i32_e32 vcc, 18, v246
	s_nop 1
	v_cndmask_b32_e32 v58, v199, v58, vcc
	v_cmp_le_i32_e32 vcc, 19, v246
	s_nop 1
	v_cndmask_b32_e32 v59, v199, v59, vcc
	v_cmp_le_i32_e32 vcc, 24, v246
	s_nop 1
	v_cndmask_b32_e32 v60, v199, v60, vcc
	v_cmp_le_i32_e32 vcc, 25, v246
	s_nop 1
	v_cndmask_b32_e32 v61, v199, v61, vcc
	v_cmp_le_i32_e32 vcc, 26, v246
	s_nop 1
	v_cndmask_b32_e32 v62, v199, v62, vcc
	v_cmp_le_i32_e32 vcc, 27, v246
	s_nop 1
	v_cndmask_b32_e32 v63, v199, v63, vcc
	s_branch .Lasel_softmax

; #define NEGINF (-__builtin_inff())
; DI int crow(int i, int h) { return (i & 3) + 8 * (i >> 2) + 4 * h; }
; DI void moba_item(const Params& p, int b, int hd, int qb, const unsigned char* blut, const float* tbl) {
;     ...
;   attn_loop(st, qf, 0, qb, 32,
;     [&](int kt) { return K + (size_t)kt * 2048 + (h * 32 + r) * 8; },
;     [&](int kt) { return Vt + (size_t)kt * 2048 + (h * 32 + r) * 4; },
;     [&](int kt) { return __ballot((mmask >> (kt >> 3)) & 1u) != 0ull; },
;     [&](int kt, const f32x16& s, float (&lg)[16]) {
;       const bool bs = (mmask >> (kt >> 3)) & 1u;
;       if (qb * 32 - (kt * 32 + 31) >= 1513) {
;         const float b31 = tblh[31];
; #pragma unroll
;         for (int i = 0; i < 16; ++i) lg[i] = bs ? s[i] + b31 : NEGINF;
;       } else {
;         int dist[16]; float bv[16];
; #pragma unroll
;         for (int i = 0; i < 16; ++i) dist[i] = t - (kt * 32 + crow(i, h));
;         bias16(blut, tblh, dist, bv);
; #pragma unroll
;         for (int i = 0; i < 16; ++i) lg[i] = (bs && dist[i] >= 0) ? s[i] + bv[i] : NEGINF;
.Lamoba_loop:
	s_waitcnt vmcnt(2)
	s_barrier
	s_lshr_b32 s23, s56, 1
	s_add_u32 s23, s23, 2
	s_sub_u32 s61, s100, 0x4000
	s_cmp_lt_u32 s61, 0x10000
	s_cselect_b32 s61, 0x18000, s61
	s_lshr_b32 s24, s59, 1
	s_min_u32 s24, s23, s24
	s_lshl_b32 s26, s24, 13
	s_lshl_b32 s24, s58, 10
	s_add_u32 s26, s26, s24
	s_mov_b32 s27, 0
	v_lshl_add_u64 v[186:187], v[134:135], 0, s[26:27]
	v_lshl_add_u64 v[218:219], v[136:137], 0, s[26:27]
	v_add_co_u32_e32 v218, vcc, v218, v185
	v_addc_co_u32_e32 v219, vcc, 0, v219, vcc
	s_add_u32 s24, s24, s61
	s_mov_b32 m0, s24
	s_nop 0
	global_load_lds_dwordx4 v[186:187], off
	s_add_u32 s24, s24, 0x2000
	s_mov_b32 m0, s24
	s_nop 0
	global_load_lds_dwordx4 v[218:219], off
	s_cmp_le_u32 s56, s60
	s_cbranch_scc0 .Lamoba_skip
	v_lshl_add_u32 v186, v185, 1, s100
	ds_read_b128 v[96:99], v186 offset:0
	ds_read_b128 v[112:115], v186 offset:4096
	ds_read_b128 v[100:103], v186 offset:1024
	ds_read_b128 v[116:119], v186 offset:5120
	ds_read_b128 v[104:107], v186 offset:2048
	ds_read_b128 v[120:123], v186 offset:6144
	ds_read_b128 v[108:111], v186 offset:3072
	ds_read_b128 v[124:127], v186 offset:7168
	s_sub_i32 s61, s60, s56
	s_lshr_b32 s23, s56, 3
	v_bfe_u32 v184, v157, s23, 1
	v_cmp_eq_u32_e64 s[62:63], 1, v184
	s_waitcnt lgkmcnt(6)
	v_mfma_f32_32x32x16_bf16 v[32:47], v[96:99], v[80:83], 0
	v_mfma_f32_32x32x16_bf16 v[48:63], v[112:115], v[80:83], 0
	s_waitcnt lgkmcnt(4)
	v_mfma_f32_32x32x16_bf16 v[32:47], v[100:103], v[84:87], v[32:47]
	v_mfma_f32_32x32x16_bf16 v[48:63], v[116:119], v[84:87], v[48:63]
	s_waitcnt lgkmcnt(2)
	v_mfma_f32_32x32x16_bf16 v[32:47], v[104:107], v[88:91], v[32:47]
	v_mfma_f32_32x32x16_bf16 v[48:63], v[120:123], v[88:91], v[48:63]
	s_waitcnt lgkmcnt(0)
	v_mfma_f32_32x32x16_bf16 v[32:47], v[108:111], v[92:95], v[32:47]
	v_mfma_f32_32x32x16_bf16 v[48:63], v[124:127], v[92:95], v[48:63]
	v_add_u32_e32 v218, s100, v185
	ds_read_b64 v[64:65], v218 offset:8192
	ds_read_b64 v[66:67], v218 offset:8704
	ds_read_b64 v[68:69], v218 offset:9216
	ds_read_b64 v[70:71], v218 offset:9728
	ds_read_b64 v[72:73], v218 offset:10240
	ds_read_b64 v[74:75], v218 offset:10752
	ds_read_b64 v[76:77], v218 offset:11264
	ds_read_b64 v[78:79], v218 offset:11776
	ds_read_b64 v[138:139], v218 offset:12288
	ds_read_b64 v[140:141], v218 offset:12800
	ds_read_b64 v[142:143], v218 offset:13312
	ds_read_b64 v[144:145], v218 offset:13824
	ds_read_b64 v[146:147], v218 offset:14336
	ds_read_b64 v[148:149], v218 offset:14848
	ds_read_b64 v[150:151], v218 offset:15360
	ds_read_b64 v[152:153], v218 offset:15872
	s_cmp_ge_i32 s61, 50
	s_cbranch_scc1 .Lamoba_far
	s_lshl_b32 s23, s61, 5
	v_add_u32_e32 v179, s23, v158
	v_lshl_add_u32 v182, v179, 2, v180
	v_subrev_u32_e32 v183, 128, v182
	ds_read_b32 v162, v182 offset:108
	ds_read_b32 v163, v182 offset:104
	ds_read_b32 v164, v182 offset:100
	ds_read_b32 v165, v182 offset:96
	ds_read_b32 v166, v182 offset:76
	ds_read_b32 v167, v182 offset:72
	ds_read_b32 v168, v182 offset:68
	ds_read_b32 v169, v182 offset:64
	ds_read_b32 v170, v182 offset:44
	ds_read_b32 v171, v182 offset:40
	ds_read_b32 v172, v182 offset:36
	ds_read_b32 v173, v182 offset:32
	ds_read_b32 v174, v182 offset:12
	ds_read_b32 v175, v182 offset:8
	ds_read_b32 v176, v182 offset:4
	ds_read_b32 v177, v182 offset:0
	s_waitcnt lgkmcnt(8)
	v_add_f32_e32 v32, v32, v162
	v_add_f32_e32 v33, v33, v163
	v_add_f32_e32 v34, v34, v164
	v_add_f32_e32 v35, v35, v165
	v_add_f32_e32 v36, v36, v166
	v_add_f32_e32 v37, v37, v167
	v_add_f32_e32 v38, v38, v168
	v_add_f32_e32 v39, v39, v169
	ds_read_b32 v162, v183 offset:108
	ds_read_b32 v163, v183 offset:104
	ds_read_b32 v164, v183 offset:100
	ds_read_b32 v165, v183 offset:96
	ds_read_b32 v166, v183 offset:76
	ds_read_b32 v167, v183 offset:72
	ds_read_b32 v168, v183 offset:68
	ds_read_b32 v169, v183 offset:64
	s_waitcnt lgkmcnt(8)
	v_add_f32_e32 v40, v40, v170
	v_add_f32_e32 v41, v41, v171
	v_add_f32_e32 v42, v42, v172
	v_add_f32_e32 v43, v43, v173
	v_add_f32_e32 v44, v44, v174
	v_add_f32_e32 v45, v45, v175
	v_add_f32_e32 v46, v46, v176
	v_add_f32_e32 v47, v47, v177
	ds_read_b32 v170, v183 offset:44
	ds_read_b32 v171, v183 offset:40
	ds_read_b32 v172, v183 offset:36
	ds_read_b32 v173, v183 offset:32
	ds_read_b32 v174, v183 offset:12
	ds_read_b32 v175, v183 offset:8
	ds_read_b32 v176, v183 offset:4
	ds_read_b32 v177, v183 offset:0
	s_waitcnt lgkmcnt(8)
	v_add_f32_e32 v48, v48, v162
	v_add_f32_e32 v49, v49, v163
	v_add_f32_e32 v50, v50, v164
	v_add_f32_e32 v51, v51, v165
	v_add_f32_e32 v52, v52, v166
	v_add_f32_e32 v53, v53, v167
	v_add_f32_e32 v54, v54, v168
	v_add_f32_e32 v55, v55, v169
	s_waitcnt lgkmcnt(0)
	v_add_f32_e32 v56, v56, v170
	v_add_f32_e32 v57, v57, v171
	v_add_f32_e32 v58, v58, v172
	v_add_f32_e32 v59, v59, v173
	v_add_f32_e32 v60, v60, v174
	v_add_f32_e32 v61, v61, v175
	v_add_f32_e32 v62, v62, v176
	v_add_f32_e32 v63, v63, v177
	s_cmp_ge_i32 s61, 2
	s_cbranch_scc1 .Lamoba_softmax
; #define NEGINF (-__builtin_inff())
; DI int crow(int i, int h) { return (i & 3) + 8 * (i >> 2) + 4 * h; }
; DI void moba_item(const Params& p, int b, int hd, int qb, const unsigned char* blut, const float* tbl) {
;     ...
;         int dist[16]; float bv[16];
; #pragma unroll
;         for (int i = 0; i < 16; ++i) dist[i] = t - (kt * 32 + crow(i, h));
;         bias16(blut, tblh, dist, bv);
; #pragma unroll
;         for (int i = 0; i < 16; ++i) lg[i] = (bs && dist[i] >= 0) ? s[i] + bv[i] : NEGINF;
	v_subrev_u32_e32 v184, 32, v179
	v_cmp_le_i32_e32 vcc, 0, v179
	s_nop 1
	v_cndmask_b32_e32 v32, v199, v32, vcc
	v_cmp_le_i32_e32 vcc, 1, v179
	s_nop 1
	v_cndmask_b32_e32 v33, v199, v33, vcc
	v_cmp_le_i32_e32 vcc, 2, v179
	s_nop 1
	v_cndmask_b32_e32 v34, v199, v34, vcc
	v_cmp_le_i32_e32 vcc, 3, v179
	s_nop 1
	v_cndmask_b32_e32 v35, v199, v35, vcc
	v_cmp_le_i32_e32 vcc, 8, v179
	s_nop 1
	v_cndmask_b32_e32 v36, v199, v36, vcc
	v_cmp_le_i32_e32 vcc, 9, v179
	s_nop 1
	v_cndmask_b32_e32 v37, v199, v37, vcc
	v_cmp_le_i32_e32 vcc, 10, v179
	s_nop 1
	v_cndmask_b32_e32 v38, v199, v38, vcc
	v_cmp_le_i32_e32 vcc, 11, v179
	s_nop 1
	v_cndmask_b32_e32 v39, v199, v39, vcc
	v_cmp_le_i32_e32 vcc, 16, v179
	s_nop 1
	v_cndmask_b32_e32 v40, v199, v40, vcc
	v_cmp_le_i32_e32 vcc, 17, v179
	s_nop 1
	v_cndmask_b32_e32 v41, v199, v41, vcc
	v_cmp_le_i32_e32 vcc, 18, v179
	s_nop 1
	v_cndmask_b32_e32 v42, v199, v42, vcc
	v_cmp_le_i32_e32 vcc, 19, v179
	s_nop 1
	v_cndmask_b32_e32 v43, v199, v43, vcc
	v_cmp_le_i32_e32 vcc, 24, v179
	s_nop 1
	v_cndmask_b32_e32 v44, v199, v44, vcc
	v_cmp_le_i32_e32 vcc, 25, v179
	s_nop 1
	v_cndmask_b32_e32 v45, v199, v45, vcc
	v_cmp_le_i32_e32 vcc, 26, v179
	s_nop 1
	v_cndmask_b32_e32 v46, v199, v46, vcc
	v_cmp_le_i32_e32 vcc, 27, v179
	s_nop 1
	v_cndmask_b32_e32 v47, v199, v47, vcc
	v_cmp_le_i32_e32 vcc, 0, v184
	s_nop 1
	v_cndmask_b32_e32 v48, v199, v48, vcc
	v_cmp_le_i32_e32 vcc, 1, v184
	s_nop 1
	v_cndmask_b32_e32 v49, v199, v49, vcc
	v_cmp_le_i32_e32 vcc, 2, v184
	s_nop 1
	v_cndmask_b32_e32 v50, v199, v50, vcc
	v_cmp_le_i32_e32 vcc, 3, v184
	s_nop 1
	v_cndmask_b32_e32 v51, v199, v51, vcc
	v_cmp_le_i32_e32 vcc, 8, v184
	s_nop 1
	v_cndmask_b32_e32 v52, v199, v52, vcc
	v_cmp_le_i32_e32 vcc, 9, v184
	s_nop 1
	v_cndmask_b32_e32 v53, v199, v53, vcc
	v_cmp_le_i32_e32 vcc, 10, v184
	s_nop 1
	v_cndmask_b32_e32 v54, v199, v54, vcc
	v_cmp_le_i32_e32 vcc, 11, v184
	s_nop 1
	v_cndmask_b32_e32 v55, v199, v55, vcc
	v_cmp_le_i32_e32 vcc, 16, v184
	s_nop 1
	v_cndmask_b32_e32 v56, v199, v56, vcc
	v_cmp_le_i32_e32 vcc, 17, v184
	s_nop 1
	v_cndmask_b32_e32 v57, v199, v57, vcc
	v_cmp_le_i32_e32 vcc, 18, v184
	s_nop 1
	v_cndmask_b32_e32 v58, v199, v58, vcc
	v_cmp_le_i32_e32 vcc, 19, v184
	s_nop 1
	v_cndmask_b32_e32 v59, v199, v59, vcc
	v_cmp_le_i32_e32 vcc, 24, v184
	s_nop 1
	v_cndmask_b32_e32 v60, v199, v60, vcc
	v_cmp_le_i32_e32 vcc, 25, v184
	s_nop 1
	v_cndmask_b32_e32 v61, v199, v61, vcc
	v_cmp_le_i32_e32 vcc, 26, v184
	s_nop 1
	v_cndmask_b32_e32 v62, v199, v62, vcc
	v_cmp_le_i32_e32 vcc, 27, v184
	s_nop 1
	v_cndmask_b32_e32 v63, v199, v63, vcc
	s_branch .Lamoba_softmax

; #define NEGINF (-__builtin_inff())
; DI int crow(int i, int h) { return (i & 3) + 8 * (i >> 2) + 4 * h; }
; DI void nsa_win_item(const Params& p, int b, int head, int qb, const unsigned char* blut, const float* tbl) {
;     ...
;     attn_loop(st, qf, k0, qb, 32,
;       [&](int kt) { return K + (size_t)kt * 2048 + (h * 32 + r) * 8; },
;       [&](int kt) { return Vt + (size_t)kt * 2048 + (h * 32 + r) * 4; },
;       [&](int kt) { return true; },
;       [&](int kt, const f32x16& s, float (&lg)[16]) {
;         int dist[16]; float bv[16];
; #pragma unroll
;         for (int i = 0; i < 16; ++i) dist[i] = t - (kt * 32 + crow(i, h));
;         bias16(blut, tblh, dist, bv);
; #pragma unroll
;         for (int i = 0; i < 16; ++i) lg[i] = (dist[i] >= 0 && dist[i] < 512) ? s[i] + bv[i] : NEGINF;
;       });
.Lawin4_loop:
	s_waitcnt vmcnt(2)
	s_barrier
	s_lshr_b32 s23, s56, 1
	s_add_u32 s23, s23, 2
	s_sub_u32 s61, s64, 0x4000
	s_cmp_lt_u32 s61, 0x10000
	s_cselect_b32 s61, 0x18000, s61
	s_lshr_b32 s24, s59, 1
	s_min_u32 s24, s23, s24
	s_lshl_b32 s26, s24, 13
	s_lshl_b32 s24, s58, 10
	s_add_u32 s26, s26, s24
	s_mov_b32 s27, 0
	v_lshl_add_u64 v[186:187], v[116:117], 0, s[26:27]
	v_lshl_add_u64 v[126:127], v[114:115], 0, s[26:27]
	v_add_co_u32_e32 v126, vcc, v126, v185
	v_addc_co_u32_e32 v127, vcc, 0, v127, vcc
	s_add_u32 s24, s24, s61
	s_mov_b32 m0, s24
	s_nop 0
	global_load_lds_dwordx4 v[186:187], off
	s_add_u32 s24, s24, 0x2000
	s_mov_b32 m0, s24
	s_nop 0
	global_load_lds_dwordx4 v[126:127], off
	s_cmp_le_u32 s56, s60
	s_cbranch_scc0 .Lawin4_skip
	s_add_u32 s24, s56, 1
	s_cmp_ge_u32 s24, s65
	s_cbranch_scc0 .Lawin4_skip
	v_lshl_add_u32 v186, v185, 1, s64
	ds_read_b128 v[80:83], v186 offset:0
	ds_read_b128 v[96:99], v186 offset:4096
	ds_read_b128 v[84:87], v186 offset:1024
	ds_read_b128 v[100:103], v186 offset:5120
	ds_read_b128 v[88:91], v186 offset:2048
	ds_read_b128 v[104:107], v186 offset:6144
	ds_read_b128 v[92:95], v186 offset:3072
	ds_read_b128 v[108:111], v186 offset:7168
	s_sub_i32 s61, s60, s56
	s_waitcnt lgkmcnt(6)
	v_mfma_f32_32x32x16_bf16 v[32:47], v[80:83], v[64:67], 0
	v_mfma_f32_32x32x16_bf16 v[48:63], v[96:99], v[64:67], 0
	s_waitcnt lgkmcnt(4)
	v_mfma_f32_32x32x16_bf16 v[32:47], v[84:87], v[68:71], v[32:47]
	v_mfma_f32_32x32x16_bf16 v[48:63], v[100:103], v[68:71], v[48:63]
	s_waitcnt lgkmcnt(2)
	v_mfma_f32_32x32x16_bf16 v[32:47], v[88:91], v[72:75], v[32:47]
	v_mfma_f32_32x32x16_bf16 v[48:63], v[104:107], v[72:75], v[48:63]
	s_waitcnt lgkmcnt(0)
	v_mfma_f32_32x32x16_bf16 v[32:47], v[92:95], v[76:79], v[32:47]
	v_mfma_f32_32x32x16_bf16 v[48:63], v[108:111], v[76:79], v[48:63]
	v_add_u32_e32 v126, s64, v185
	ds_read_b64 v[146:147], v126 offset:8192
	ds_read_b64 v[148:149], v126 offset:8704
	ds_read_b64 v[150:151], v126 offset:9216
	ds_read_b64 v[152:153], v126 offset:9728
	ds_read_b64 v[154:155], v126 offset:10240
	ds_read_b64 v[156:157], v126 offset:10752
	ds_read_b64 v[158:159], v126 offset:11264
	ds_read_b64 v[160:161], v126 offset:11776
	ds_read_b64 v[162:163], v126 offset:12288
	ds_read_b64 v[164:165], v126 offset:12800
	ds_read_b64 v[166:167], v126 offset:13312
	ds_read_b64 v[168:169], v126 offset:13824
	ds_read_b64 v[170:171], v126 offset:14336
	ds_read_b64 v[172:173], v126 offset:14848
	ds_read_b64 v[174:175], v126 offset:15360
	ds_read_b64 v[176:177], v126 offset:15872
	s_cmp_ge_i32 s61, 50
	s_cbranch_scc1 .Lawin4_far
	s_lshl_b32 s23, s61, 5
	v_add_u32_e32 v179, s23, v142
	v_lshl_add_u32 v182, v179, 2, v180
	v_subrev_u32_e32 v183, 128, v182
	ds_read_b32 v118, v182 offset:108
	ds_read_b32 v119, v182 offset:104
	ds_read_b32 v120, v182 offset:100
	ds_read_b32 v121, v182 offset:96
	ds_read_b32 v122, v182 offset:76
	ds_read_b32 v123, v182 offset:72
	ds_read_b32 v124, v182 offset:68
	ds_read_b32 v125, v182 offset:64
	ds_read_b32 v132, v182 offset:44
	ds_read_b32 v133, v182 offset:40
	ds_read_b32 v134, v182 offset:36
	ds_read_b32 v135, v182 offset:32
	ds_read_b32 v218, v182 offset:12
	ds_read_b32 v219, v182 offset:8
	ds_read_b32 v220, v182 offset:4
	ds_read_b32 v221, v182 offset:0
	s_waitcnt lgkmcnt(8)
	v_add_f32_e32 v32, v32, v118
	v_add_f32_e32 v33, v33, v119
	v_add_f32_e32 v34, v34, v120
	v_add_f32_e32 v35, v35, v121
	v_add_f32_e32 v36, v36, v122
	v_add_f32_e32 v37, v37, v123
	v_add_f32_e32 v38, v38, v124
	v_add_f32_e32 v39, v39, v125
	ds_read_b32 v118, v183 offset:108
	ds_read_b32 v119, v183 offset:104
	ds_read_b32 v120, v183 offset:100
	ds_read_b32 v121, v183 offset:96
	ds_read_b32 v122, v183 offset:76
	ds_read_b32 v123, v183 offset:72
	ds_read_b32 v124, v183 offset:68
	ds_read_b32 v125, v183 offset:64
	s_waitcnt lgkmcnt(8)
	v_add_f32_e32 v40, v40, v132
	v_add_f32_e32 v41, v41, v133
	v_add_f32_e32 v42, v42, v134
	v_add_f32_e32 v43, v43, v135
	v_add_f32_e32 v44, v44, v218
	v_add_f32_e32 v45, v45, v219
	v_add_f32_e32 v46, v46, v220
	v_add_f32_e32 v47, v47, v221
	ds_read_b32 v132, v183 offset:44
	ds_read_b32 v133, v183 offset:40
	ds_read_b32 v134, v183 offset:36
	ds_read_b32 v135, v183 offset:32
	ds_read_b32 v218, v183 offset:12
	ds_read_b32 v219, v183 offset:8
	ds_read_b32 v220, v183 offset:4
	ds_read_b32 v221, v183 offset:0
	s_waitcnt lgkmcnt(8)
	v_add_f32_e32 v48, v48, v118
	v_add_f32_e32 v49, v49, v119
	v_add_f32_e32 v50, v50, v120
	v_add_f32_e32 v51, v51, v121
	v_add_f32_e32 v52, v52, v122
	v_add_f32_e32 v53, v53, v123
	v_add_f32_e32 v54, v54, v124
	v_add_f32_e32 v55, v55, v125
	s_waitcnt lgkmcnt(0)
	v_add_f32_e32 v56, v56, v132
	v_add_f32_e32 v57, v57, v133
	v_add_f32_e32 v58, v58, v134
	v_add_f32_e32 v59, v59, v135
	v_add_f32_e32 v60, v60, v218
	v_add_f32_e32 v61, v61, v219
	v_add_f32_e32 v62, v62, v220
	v_add_f32_e32 v63, v63, v221
	s_cmp_ge_i32 s61, 15
	s_cbranch_scc0 .Lawin4_nowin
; #define NEGINF (-__builtin_inff())
; DI int crow(int i, int h) { return (i & 3) + 8 * (i >> 2) + 4 * h; }
; DI void nsa_win_item(const Params& p, int b, int head, int qb, const unsigned char* blut, const float* tbl) {
;     ...
;       [&](int kt, const f32x16& s, float (&lg)[16]) {
;         int dist[16]; float bv[16];
; #pragma unroll
;         for (int i = 0; i < 16; ++i) dist[i] = t - (kt * 32 + crow(i, h));
;         bias16(blut, tblh, dist, bv);
; #pragma unroll
;         for (int i = 0; i < 16; ++i) lg[i] = (dist[i] >= 0 && dist[i] < 512) ? s[i] + bv[i] : NEGINF;
;       });
	v_subrev_u32_e32 v184, 32, v179
	v_cmp_gt_i32_e32 vcc, 0x200, v179
	s_nop 1
	v_cndmask_b32_e32 v32, v199, v32, vcc
	v_cmp_gt_i32_e32 vcc, 0x201, v179
	s_nop 1
	v_cndmask_b32_e32 v33, v199, v33, vcc
	v_cmp_gt_i32_e32 vcc, 0x202, v179
	s_nop 1
	v_cndmask_b32_e32 v34, v199, v34, vcc
	v_cmp_gt_i32_e32 vcc, 0x203, v179
	s_nop 1
	v_cndmask_b32_e32 v35, v199, v35, vcc
	v_cmp_gt_i32_e32 vcc, 0x208, v179
	s_nop 1
	v_cndmask_b32_e32 v36, v199, v36, vcc
	v_cmp_gt_i32_e32 vcc, 0x209, v179
	s_nop 1
	v_cndmask_b32_e32 v37, v199, v37, vcc
	v_cmp_gt_i32_e32 vcc, 0x20a, v179
	s_nop 1
	v_cndmask_b32_e32 v38, v199, v38, vcc
	v_cmp_gt_i32_e32 vcc, 0x20b, v179
	s_nop 1
	v_cndmask_b32_e32 v39, v199, v39, vcc
	v_cmp_gt_i32_e32 vcc, 0x210, v179
	s_nop 1
	v_cndmask_b32_e32 v40, v199, v40, vcc
	v_cmp_gt_i32_e32 vcc, 0x211, v179
	s_nop 1
	v_cndmask_b32_e32 v41, v199, v41, vcc
	v_cmp_gt_i32_e32 vcc, 0x212, v179
	s_nop 1
	v_cndmask_b32_e32 v42, v199, v42, vcc
	v_cmp_gt_i32_e32 vcc, 0x213, v179
	s_nop 1
	v_cndmask_b32_e32 v43, v199, v43, vcc
	v_cmp_gt_i32_e32 vcc, 0x218, v179
	s_nop 1
	v_cndmask_b32_e32 v44, v199, v44, vcc
	v_cmp_gt_i32_e32 vcc, 0x219, v179
	s_nop 1
	v_cndmask_b32_e32 v45, v199, v45, vcc
	v_cmp_gt_i32_e32 vcc, 0x21a, v179
	s_nop 1
	v_cndmask_b32_e32 v46, v199, v46, vcc
	v_cmp_gt_i32_e32 vcc, 0x21b, v179
	s_nop 1
	v_cndmask_b32_e32 v47, v199, v47, vcc
	v_cmp_gt_i32_e32 vcc, 0x200, v184
	s_nop 1
	v_cndmask_b32_e32 v48, v199, v48, vcc
	v_cmp_gt_i32_e32 vcc, 0x201, v184
	s_nop 1
	v_cndmask_b32_e32 v49, v199, v49, vcc
	v_cmp_gt_i32_e32 vcc, 0x202, v184
	s_nop 1
	v_cndmask_b32_e32 v50, v199, v50, vcc
	v_cmp_gt_i32_e32 vcc, 0x203, v184
	s_nop 1
	v_cndmask_b32_e32 v51, v199, v51, vcc
	v_cmp_gt_i32_e32 vcc, 0x208, v184
	s_nop 1
	v_cndmask_b32_e32 v52, v199, v52, vcc
	v_cmp_gt_i32_e32 vcc, 0x209, v184
	s_nop 1
	v_cndmask_b32_e32 v53, v199, v53, vcc
	v_cmp_gt_i32_e32 vcc, 0x20a, v184
	s_nop 1
	v_cndmask_b32_e32 v54, v199, v54, vcc
	v_cmp_gt_i32_e32 vcc, 0x20b, v184
	s_nop 1
	v_cndmask_b32_e32 v55, v199, v55, vcc
	v_cmp_gt_i32_e32 vcc, 0x210, v184
	s_nop 1
	v_cndmask_b32_e32 v56, v199, v56, vcc
	v_cmp_gt_i32_e32 vcc, 0x211, v184
	s_nop 1
	v_cndmask_b32_e32 v57, v199, v57, vcc
	v_cmp_gt_i32_e32 vcc, 0x212, v184
	s_nop 1
	v_cndmask_b32_e32 v58, v199, v58, vcc
	v_cmp_gt_i32_e32 vcc, 0x213, v184
	s_nop 1
	v_cndmask_b32_e32 v59, v199, v59, vcc
	v_cmp_gt_i32_e32 vcc, 0x218, v184
	s_nop 1
	v_cndmask_b32_e32 v60, v199, v60, vcc
	v_cmp_gt_i32_e32 vcc, 0x219, v184
	s_nop 1
	v_cndmask_b32_e32 v61, v199, v61, vcc
	v_cmp_gt_i32_e32 vcc, 0x21a, v184
	s_nop 1
	v_cndmask_b32_e32 v62, v199, v62, vcc
	v_cmp_gt_i32_e32 vcc, 0x21b, v184
	s_nop 1
	v_cndmask_b32_e32 v63, v199, v63, vcc
